# attention: raised priority now spans K-fragment reads, QK chain, row-max and the first half of exp, until the first PV MFMA issues
# speedup vs baseline: 1.0102x; 1.0030x over previous
; template <int DK, bool PF>
; DEV void attn_item(const u16* __restrict__ qrow, const u16* __restrict__ ka, int ldka, const u16* __restrict__ kb, int ldkb,
;                    const u16* __restrict__ vt, int ldvt, int ntiles, int my_tiles, int kvlen, u16* orow,
;                    unsigned char* smem) {
;     ...
;         union { bf16x8 v[2]; unsigned u[8]; } pfu;
;         float ps = 0.f;
; #pragma unroll
;         for (int r = 0; r < 16; r += 2) {
;           float p0 = __builtin_amdgcn_exp2f(s[r] - mrun);
;           float p1 = __builtin_amdgcn_exp2f(s[r + 1] - mrun);
;           ps += p0 + p1;
;           pfu.u[r >> 1] = pk2bf(p0, p1);
;         }
;         lrun += ps;
; #pragma unroll
;         for (int oc = 0; oc < 2; ++oc)
; #pragma unroll
;           for (int d = 0; d < 4; ++d) o[d] = __builtin_amdgcn_mfma_f32_32x32x16_bf16(vf[oc * 4 + d], pfu.v[oc], o[d], 0, 0, 0);
;       }
.LBB0_1020:
	v_sub_f32_e32 v64, v64, v219
	v_exp_f32_e32 v223, v64
	v_sub_f32_e32 v64, v65, v219
	v_exp_f32_e32 v227, v64
	v_sub_f32_e32 v64, v66, v219
	v_exp_f32_e32 v222, v64
	v_sub_f32_e32 v64, v67, v219
	v_exp_f32_e32 v226, v64
	v_sub_f32_e32 v64, v68, v219
	v_exp_f32_e32 v229, v64
	v_sub_f32_e32 v64, v69, v219
	v_exp_f32_e32 v69, v64
	v_sub_f32_e32 v64, v70, v219
	v_exp_f32_e32 v228, v64
	v_sub_f32_e32 v64, v71, v219
	v_exp_f32_e32 v68, v64
	v_sub_f32_e32 v70, v72, v219
	v_cvt_pk_bf16_f32 v64, v223, v227
	v_cvt_pk_bf16_f32 v65, v222, v226
	v_cvt_pk_bf16_f32 v66, v229, v69
	v_cvt_pk_bf16_f32 v67, v228, v68
	v_exp_f32_e32 v71, v70
	v_sub_f32_e32 v70, v73, v219
	v_mfma_f32_32x32x16_bf16 v[48:63], v[192:195], v[64:67], v[48:63]
	s_setprio 0
	v_exp_f32_e32 v73, v70
	v_sub_f32_e32 v70, v74, v219
	v_sub_f32_e32 v74, v76, v219
	v_sub_f32_e32 v72, v75, v219
	v_exp_f32_e32 v75, v74
	v_sub_f32_e32 v74, v77, v219
	v_exp_f32_e32 v77, v74
	v_mfma_f32_32x32x16_bf16 v[32:47], v[196:199], v[64:67], v[32:47]
	v_sub_f32_e32 v74, v78, v219
	v_exp_f32_e32 v70, v70
	v_exp_f32_e32 v72, v72
	v_exp_f32_e32 v74, v74
	v_add_f32_e32 v68, v228, v68
	v_add_f32_e32 v69, v229, v69
	s_xor_b64 s[10:11], s[10:11], -1
	s_mov_b32 s13, 32
	v_mfma_f32_32x32x16_bf16 v[16:31], v[188:191], v[64:67], v[16:31]
	s_andn2_b64 vcc, exec, s[10:11]
	s_mov_b64 s[10:11], 0
	v_mfma_f32_32x32x16_bf16 v[0:15], v[184:187], v[64:67], v[0:15]
	v_sub_f32_e32 v64, v79, v219
	v_exp_f32_e32 v76, v64
	v_add_f32_e32 v78, v222, v226
	v_add_f32_e32 v79, v223, v227
	v_cvt_pk_bf16_f32 v64, v71, v73
	v_cvt_pk_bf16_f32 v65, v70, v72
	v_cvt_pk_bf16_f32 v66, v75, v77
	v_cvt_pk_bf16_f32 v67, v74, v76
	v_add_f32_e32 v70, v70, v72
	v_add_f32_e32 v71, v71, v73
	v_add_f32_e32 v72, v74, v76
	v_add_f32_e32 v73, v75, v77
	v_add_f32_e32 v74, 0, v79
	v_mfma_f32_32x32x16_bf16 v[48:63], v[176:179], v[64:67], v[48:63]
	v_add_f32_e32 v74, v78, v74
	v_add_f32_e32 v69, v69, v74
	v_add_f32_e32 v68, v68, v69
	v_add_f32_e32 v68, v71, v68
	v_add_f32_e32 v68, v70, v68
	v_add_f32_e32 v68, v73, v68
	v_add_f32_e32 v68, v72, v68
	v_mfma_f32_32x32x16_bf16 v[32:47], v[180:183], v[64:67], v[32:47]
	v_add_f32_e32 v215, v215, v68
	v_mfma_f32_32x32x16_bf16 v[16:31], v[172:175], v[64:67], v[16:31]
	v_mfma_f32_32x32x16_bf16 v[0:15], v[168:171], v[64:67], v[0:15]
	s_cbranch_vccz .LBB0_1023
; template <int DK, bool PF>
; DEV void attn_item(const u16* __restrict__ qrow, const u16* __restrict__ ka, int ldka, const u16* __restrict__ kb, int ldkb,
;                    const u16* __restrict__ vt, int ldvt, int ntiles, int my_tiles, int kvlen, u16* orow,
;                    unsigned char* smem) {
;     ...
;         const u16* kp = sK + (mi * 32 + l31) * KST + hh * 8;
;         constexpr int KB = QREG ? 12 : 4;
; #pragma unroll
;         for (int k0 = 0; k0 < DK / 16; k0 += KB) {
;           bf16x8 kf[KB];
; #pragma unroll
;           for (int i = 0; i < KB; ++i) kf[i] = *(const bf16x8*)(kp + (k0 + i) * 16);
;           __builtin_amdgcn_sched_barrier(0);
; #pragma unroll
;           for (int i = 0; i < KB; ++i) {
;             bf16x8 qv;
;             if (QREG) qv = qf[k0 + i];
;             else qv = *(const bf16x8*)(qp + (k0 + i) * 16);
;             s = __builtin_amdgcn_mfma_f32_32x32x16_bf16(kf[i], qv, s, 0, 0, 0);
;           }
;         }
;         bf16x8 vf[8];
;         {
;           const u16* vp = sV + l31 * VST + mi * 32 + 4 * hh;
; #pragma unroll
;           for (int oc = 0; oc < 2; ++oc)
; #pragma unroll
;             for (int d = 0; d < 4; ++d) {
;               union { bf16x8 v; uint2 u[2]; } cv;
;               cv.u[0] = *(const uint2*)(vp + d * 32 * VST + oc * 16);
;               cv.u[1] = *(const uint2*)(vp + d * 32 * VST + oc * 16 + 8);
;               vf[oc * 4 + d] = cv.v;
;             }
;           __builtin_amdgcn_sched_barrier(0);
;         }
;         if (key0 + 64 > kvlen) {
; #pragma unroll
;           for (int r = 0; r < 16; ++r) {
;             int key = key0 + mi * 32 + (r & 3) + 8 * (r >> 2) + 4 * hh;
;             if (key >= kvlen) s[r] = -1e30f;
;           }
;         }
;         float mx = -1e30f;
; #pragma unroll
;         for (int r = 0; r < 16; ++r) mx = fmaxf(mx, s[r]);
;         mx = fmaxf(mx, __shfl_xor(mx, 32, 64));
;         if (__builtin_amdgcn_ballot_w64(mx > mrun) != 0ull) {
;           const float mnew = fmaxf(mrun, mx);
;           const float alpha = __builtin_amdgcn_exp2f(mrun - mnew);
;           mrun = mnew;
;           lrun *= alpha;
; #pragma unroll
;           for (int d = 0; d < 4; ++d)
; #pragma unroll
;             for (int r = 0; r < 16; ++r) o[d][r] *= alpha;
;         }
.LBB0_1021:
	s_setprio 1
	v_or_b32_e32 v64, s13, v217
	v_mad_u32_u24 v68, v64, s54, v224
	ds_read_b128 v[64:67], v68
	ds_read_b128 v[168:171], v68 offset:32
	ds_read_b128 v[172:175], v68 offset:64
	ds_read_b128 v[176:179], v68 offset:96
	ds_read_b128 v[180:183], v68 offset:128
	ds_read_b128 v[184:187], v68 offset:160
	ds_read_b128 v[188:191], v68 offset:192
	ds_read_b128 v[192:195], v68 offset:224
	ds_read_b128 v[196:199], v68 offset:256
	ds_read_b128 v[226:229], v68 offset:288
	ds_read_b128 v[248:251], v68 offset:320
	ds_read_b128 v[234:237], v68 offset:352
	s_waitcnt lgkmcnt(11)
	v_mfma_f32_32x32x16_bf16 v[64:79], v[64:67], v[80:83], 0
	s_waitcnt lgkmcnt(10)
	v_mfma_f32_32x32x16_bf16 v[64:79], v[168:171], v[84:87], v[64:79]
	v_lshl_add_u32 v168, s13, 1, v213
	v_add_u32_e32 v169, 0x6000, v168
	v_add_u32_e32 v170, 0x8000, v168
	s_waitcnt lgkmcnt(9)
	v_mfma_f32_32x32x16_bf16 v[64:79], v[172:175], v[88:91], v[64:79]
	s_waitcnt lgkmcnt(8)
	v_mfma_f32_32x32x16_bf16 v[64:79], v[176:179], v[92:95], v[64:79]
	s_waitcnt lgkmcnt(7)
	v_mfma_f32_32x32x16_bf16 v[64:79], v[180:183], v[96:99], v[64:79]
	s_waitcnt lgkmcnt(6)
	v_mfma_f32_32x32x16_bf16 v[64:79], v[184:187], v[100:103], v[64:79]
	s_waitcnt lgkmcnt(5)
	v_mfma_f32_32x32x16_bf16 v[64:79], v[188:191], v[104:107], v[64:79]
	s_waitcnt lgkmcnt(4)
	v_mfma_f32_32x32x16_bf16 v[64:79], v[192:195], v[108:111], v[64:79]
	ds_read2_b64 v[192:195], v169 offset0:128 offset1:130
	ds_read2_b64 v[176:179], v169 offset0:132 offset1:134
	v_add_u32_e32 v169, 0x7000, v168
	v_add_u32_e32 v168, 0x9000, v168
	ds_read2_b64 v[188:191], v170 offset0:192 offset1:194
	s_waitcnt lgkmcnt(6)
	v_mfma_f32_32x32x16_bf16 v[64:79], v[196:199], v[112:115], v[64:79]
	ds_read2_b64 v[196:199], v169 offset0:160 offset1:162
	ds_read2_b64 v[184:187], v168 offset0:224 offset1:226
	ds_read2_b64 v[180:183], v169 offset0:164 offset1:166
	ds_read2_b64 v[172:175], v170 offset0:196 offset1:198
	ds_read2_b64 v[168:171], v168 offset0:228 offset1:230
	s_waitcnt lgkmcnt(10)
	v_mfma_f32_32x32x16_bf16 v[64:79], v[226:229], v[116:119], v[64:79]
	s_waitcnt lgkmcnt(9)
	v_mfma_f32_32x32x16_bf16 v[64:79], v[248:251], v[120:123], v[64:79]
	s_waitcnt lgkmcnt(8)
	v_mfma_f32_32x32x16_bf16 v[64:79], v[234:237], v[124:127], v[64:79]
	s_nop 11
	v_max3_f32 v221, v64, s53, v65
	v_max3_f32 v221, v221, v66, v67
	v_max3_f32 v221, v221, v68, v69
	v_max3_f32 v221, v221, v70, v71
	v_max3_f32 v221, v221, v72, v73
	v_max3_f32 v221, v221, v74, v75
	v_max3_f32 v221, v221, v76, v77
	v_max3_f32 v221, v221, v78, v79
	ds_bpermute_b32 v222, v220, v221
	s_waitcnt lgkmcnt(0)
	v_max_f32_e32 v222, v222, v222
	v_max_f32_e32 v221, v221, v222
	v_cmp_gt_f32_e32 vcc, v221, v219
	s_cbranch_vccz .LBB0_1020
	v_max_f32_e32 v221, v221, v221
	v_max_f32_e32 v222, v219, v219
	v_max_f32_e32 v221, v222, v221
	v_sub_f32_e32 v219, v219, v221
	v_exp_f32_e32 v222, v219
	v_mov_b32_e32 v219, v221
	v_pk_mul_f32 v[62:63], v[62:63], v[222:223] op_sel_hi:[1,0]
	v_pk_mul_f32 v[60:61], v[60:61], v[222:223] op_sel_hi:[1,0]
	v_pk_mul_f32 v[58:59], v[58:59], v[222:223] op_sel_hi:[1,0]
	v_pk_mul_f32 v[56:57], v[56:57], v[222:223] op_sel_hi:[1,0]
	v_pk_mul_f32 v[54:55], v[54:55], v[222:223] op_sel_hi:[1,0]
	v_pk_mul_f32 v[52:53], v[52:53], v[222:223] op_sel_hi:[1,0]
	v_pk_mul_f32 v[50:51], v[50:51], v[222:223] op_sel_hi:[1,0]
	v_pk_mul_f32 v[48:49], v[48:49], v[222:223] op_sel_hi:[1,0]
	v_pk_mul_f32 v[46:47], v[46:47], v[222:223] op_sel_hi:[1,0]
	v_pk_mul_f32 v[44:45], v[44:45], v[222:223] op_sel_hi:[1,0]
	v_pk_mul_f32 v[42:43], v[42:43], v[222:223] op_sel_hi:[1,0]
	v_pk_mul_f32 v[40:41], v[40:41], v[222:223] op_sel_hi:[1,0]
	v_pk_mul_f32 v[38:39], v[38:39], v[222:223] op_sel_hi:[1,0]
	v_pk_mul_f32 v[36:37], v[36:37], v[222:223] op_sel_hi:[1,0]
	v_pk_mul_f32 v[34:35], v[34:35], v[222:223] op_sel_hi:[1,0]
	v_pk_mul_f32 v[32:33], v[32:33], v[222:223] op_sel_hi:[1,0]
	v_pk_mul_f32 v[30:31], v[30:31], v[222:223] op_sel_hi:[1,0]
	v_pk_mul_f32 v[28:29], v[28:29], v[222:223] op_sel_hi:[1,0]
	v_pk_mul_f32 v[26:27], v[26:27], v[222:223] op_sel_hi:[1,0]
	v_pk_mul_f32 v[24:25], v[24:25], v[222:223] op_sel_hi:[1,0]
	v_pk_mul_f32 v[22:23], v[22:23], v[222:223] op_sel_hi:[1,0]
	v_pk_mul_f32 v[20:21], v[20:21], v[222:223] op_sel_hi:[1,0]
	v_pk_mul_f32 v[18:19], v[18:19], v[222:223] op_sel_hi:[1,0]
	v_pk_mul_f32 v[16:17], v[16:17], v[222:223] op_sel_hi:[1,0]
	v_pk_mul_f32 v[14:15], v[14:15], v[222:223] op_sel_hi:[1,0]
	v_pk_mul_f32 v[12:13], v[12:13], v[222:223] op_sel_hi:[1,0]
	v_pk_mul_f32 v[10:11], v[10:11], v[222:223] op_sel_hi:[1,0]
	v_pk_mul_f32 v[8:9], v[8:9], v[222:223] op_sel_hi:[1,0]
	v_pk_mul_f32 v[6:7], v[6:7], v[222:223] op_sel_hi:[1,0]
	v_pk_mul_f32 v[4:5], v[4:5], v[222:223] op_sel_hi:[1,0]
	v_pk_mul_f32 v[2:3], v[2:3], v[222:223] op_sel_hi:[1,0]
	v_pk_mul_f32 v[0:1], v[0:1], v[222:223] op_sel_hi:[1,0]
	v_mul_f32_e32 v215, v215, v222
	s_branch .LBB0_1020
